# spatial gMLP phase: v-tile staging loads and b_spatial loads issued together instead of one round trip each
# speedup vs baseline: 1.0743x; 1.0002x over previous
.LBB0_215:
	s_or_b64 exec, exec, s[2:3]
	v_add_u32_e32 v0, s13, v72
	v_ashrrev_i32_e32 v1, 31, v0
	v_lshlrev_b64 v[0:1], 8, v[0:1]
	v_lshl_add_u64 v[4:5], v[62:63], 0, v[0:1]
	global_load_dwordx4 v[0:3], v[4:5], off
	global_load_dwordx4 v[56:59], v[4:5], off offset:32
	global_load_dwordx4 v[52:55], v[4:5], off offset:64
	global_load_dwordx4 v[48:51], v[4:5], off offset:96
	global_load_dwordx4 v[44:47], v[4:5], off offset:128
	global_load_dwordx4 v[40:43], v[4:5], off offset:160
	global_load_dwordx4 v[36:39], v[4:5], off offset:192
	global_load_dwordx4 v[32:35], v[4:5], off offset:224
	v_add_u32_e32 v4, s12, v73
	v_or_b32_e32 v110, 25, v4
	v_ashrrev_i32_e32 v111, 31, v110
	v_lshl_add_u64 v[6:7], v[64:65], 0, s[96:97]
	v_ashrrev_i32_e32 v5, 31, v4
	v_lshlrev_b64 v[110:111], 11, v[110:111]
	v_lshlrev_b64 v[68:69], 11, v[4:5]
	v_or_b32_e32 v10, 1, v4
	v_or_b32_e32 v12, 2, v4
	v_or_b32_e32 v14, 3, v4
	v_or_b32_e32 v16, 8, v4
	v_or_b32_e32 v18, 9, v4
	v_or_b32_e32 v20, 10, v4
	v_or_b32_e32 v22, 11, v4
	v_or_b32_e32 v24, 16, v4
	v_or_b32_e32 v26, 17, v4
	v_or_b32_e32 v28, 18, v4
	v_or_b32_e32 v30, 19, v4
	v_or_b32_e32 v108, 24, v4
	v_lshl_add_u64 v[140:141], v[6:7], 0, v[110:111]
	v_or_b32_e32 v110, 26, v4
	v_or_b32_e32 v4, 27, v4
	v_ashrrev_i32_e32 v11, 31, v10
	v_ashrrev_i32_e32 v109, 31, v108
	v_ashrrev_i32_e32 v5, 31, v4
	v_lshlrev_b64 v[10:11], 11, v[10:11]
	v_ashrrev_i32_e32 v13, 31, v12
	v_ashrrev_i32_e32 v15, 31, v14
	v_ashrrev_i32_e32 v17, 31, v16
	v_ashrrev_i32_e32 v19, 31, v18
	v_ashrrev_i32_e32 v21, 31, v20
	v_ashrrev_i32_e32 v23, 31, v22
	v_ashrrev_i32_e32 v25, 31, v24
	v_ashrrev_i32_e32 v27, 31, v26
	v_ashrrev_i32_e32 v29, 31, v28
	v_ashrrev_i32_e32 v31, 31, v30
	v_lshlrev_b64 v[108:109], 11, v[108:109]
	v_ashrrev_i32_e32 v111, 31, v110
	v_lshlrev_b64 v[4:5], 11, v[4:5]
	v_lshl_add_u64 v[8:9], v[6:7], 0, v[68:69]
	v_lshl_add_u64 v[10:11], v[6:7], 0, v[10:11]
	v_lshlrev_b64 v[12:13], 11, v[12:13]
	v_lshlrev_b64 v[14:15], 11, v[14:15]
	v_lshlrev_b64 v[16:17], 11, v[16:17]
	v_lshlrev_b64 v[18:19], 11, v[18:19]
	v_lshlrev_b64 v[20:21], 11, v[20:21]
	v_lshlrev_b64 v[22:23], 11, v[22:23]
	v_lshlrev_b64 v[24:25], 11, v[24:25]
	v_lshlrev_b64 v[26:27], 11, v[26:27]
	v_lshlrev_b64 v[28:29], 11, v[28:29]
	v_lshlrev_b64 v[30:31], 11, v[30:31]
	v_lshl_add_u64 v[108:109], v[6:7], 0, v[108:109]
	v_lshlrev_b64 v[110:111], 11, v[110:111]
	v_lshl_add_u64 v[4:5], v[6:7], 0, v[4:5]
	v_lshl_add_u64 v[12:13], v[6:7], 0, v[12:13]
	v_lshl_add_u64 v[14:15], v[6:7], 0, v[14:15]
	v_lshl_add_u64 v[16:17], v[6:7], 0, v[16:17]
	v_lshl_add_u64 v[18:19], v[6:7], 0, v[18:19]
	v_lshl_add_u64 v[20:21], v[6:7], 0, v[20:21]
	v_lshl_add_u64 v[22:23], v[6:7], 0, v[22:23]
	v_lshl_add_u64 v[24:25], v[6:7], 0, v[24:25]
	v_lshl_add_u64 v[26:27], v[6:7], 0, v[26:27]
	v_lshl_add_u64 v[28:29], v[6:7], 0, v[28:29]
	v_lshl_add_u64 v[30:31], v[6:7], 0, v[30:31]
	v_lshl_add_u64 v[142:143], v[6:7], 0, v[110:111]
	global_load_ushort v137, v[8:9], off
	global_load_ushort v138, v[8:9], off offset:64
	global_load_ushort v135, v[10:11], off
	global_load_ushort v136, v[10:11], off offset:64
	global_load_ushort v133, v[12:13], off
	global_load_ushort v134, v[12:13], off offset:64
	global_load_ushort v131, v[14:15], off
	global_load_ushort v132, v[14:15], off offset:64
	global_load_ushort v129, v[16:17], off
	global_load_ushort v130, v[16:17], off offset:64
	global_load_ushort v127, v[18:19], off
	global_load_ushort v128, v[18:19], off offset:64
	global_load_ushort v125, v[20:21], off
	global_load_ushort v126, v[20:21], off offset:64
	global_load_ushort v123, v[22:23], off
	global_load_ushort v124, v[22:23], off offset:64
	global_load_ushort v121, v[24:25], off
	global_load_ushort v122, v[24:25], off offset:64
	global_load_ushort v119, v[26:27], off
	global_load_ushort v120, v[26:27], off offset:64
	global_load_ushort v117, v[28:29], off
	global_load_ushort v118, v[28:29], off offset:64
	global_load_ushort v115, v[30:31], off
	global_load_ushort v116, v[30:31], off offset:64
	global_load_ushort v113, v[108:109], off
	global_load_ushort v114, v[108:109], off offset:64
	global_load_ushort v111, v[140:141], off
	global_load_ushort v112, v[140:141], off offset:64
	s_nop 0
	global_load_ushort v109, v[142:143], off
	global_load_ushort v110, v[142:143], off offset:64
	global_load_ushort v107, v[4:5], off
	global_load_ushort v108, v[4:5], off offset:64
	s_waitcnt lgkmcnt(0)
	s_barrier
	ds_read_b128 v[4:7], v79 offset:34816
	ds_read_b128 v[8:11], v79 offset:34832
	v_readlane_b32 s0, v254, 29
	s_add_i32 s6, s6, s7
	s_waitcnt vmcnt(39)
	v_lshlrev_b32_e32 v12, 16, v0
	v_and_b32_e32 v13, 0xffff0000, v0
	v_lshlrev_b32_e32 v0, 16, v1
	v_and_b32_e32 v1, 0xffff0000, v1
	s_waitcnt lgkmcnt(1)
	v_pk_mul_f32 v[6:7], v[6:7], v[0:1]
	v_lshlrev_b32_e32 v0, 16, v2
	v_and_b32_e32 v1, 0xffff0000, v2
	s_waitcnt lgkmcnt(0)
	v_pk_mul_f32 v[8:9], v[8:9], v[0:1]
	v_lshlrev_b32_e32 v0, 16, v3
	v_and_b32_e32 v1, 0xffff0000, v3
	v_pk_mul_f32 v[4:5], v[4:5], v[12:13]
	v_pk_mul_f32 v[10:11], v[10:11], v[0:1]
	v_cvt_pk_bf16_f32 v0, v4, v5
	v_cvt_pk_bf16_f32 v1, v6, v7
	v_cvt_pk_bf16_f32 v2, v8, v9
	v_cvt_pk_bf16_f32 v3, v10, v11
	ds_read_u16 v4, v80
	ds_read_u16 v8, v80 offset:64
	ds_read_u16 v9, v80 offset:272
	ds_read_u16 v10, v80 offset:336
	ds_read_u16 v5, v80 offset:544
	ds_read_u16 v11, v80 offset:608
	ds_read_u16 v12, v80 offset:816
	ds_read_u16 v13, v80 offset:880
	ds_read_u16 v6, v80 offset:1088
	ds_read_u16 v14, v80 offset:1152
	ds_read_u16 v15, v80 offset:1360
	ds_read_u16 v139, v80 offset:1424
	ds_read_u16 v7, v80 offset:1632
	ds_read_u16 v140, v80 offset:1696
	ds_read_u16 v16, v80 offset:1904
	ds_read_u16 v141, v80 offset:1968
	s_waitcnt lgkmcnt(5)
	v_perm_b32 v6, v15, v6, s48
	v_perm_b32 v5, v12, v5, s48
	v_perm_b32 v4, v9, v4, s48
	s_waitcnt lgkmcnt(1)
	v_perm_b32 v7, v16, v7, s48
	s_waitcnt vmcnt(38)
	v_lshlrev_b32_e32 v148, 16, v56
	v_and_b32_e32 v149, 0xffff0000, v56
	v_mfma_f32_32x32x16_bf16 v[16:31], v[0:3], v[4:7], 0
	s_waitcnt lgkmcnt(0)
	v_perm_b32 v7, v141, v140, s48
	ds_read_b128 v[140:143], v79 offset:34880
	ds_read_b128 v[144:147], v79 offset:34896
	v_lshlrev_b32_e32 v56, 16, v57
	v_and_b32_e32 v57, 0xffff0000, v57
	v_perm_b32 v6, v139, v14, s48
	v_perm_b32 v5, v13, v11, s48
	v_perm_b32 v4, v10, v8, s48
	s_waitcnt lgkmcnt(1)
	v_pk_mul_f32 v[142:143], v[142:143], v[56:57]
	v_lshlrev_b32_e32 v56, 16, v58
	v_and_b32_e32 v57, 0xffff0000, v58
	v_mfma_f32_32x32x16_bf16 v[0:15], v[0:3], v[4:7], 0
	s_waitcnt lgkmcnt(0)
	v_mul_f32_e64 v144, v144, v56
	v_mul_f32_e64 v145, v145, v57
	v_lshlrev_b32_e32 v56, 16, v59
	v_and_b32_e32 v57, 0xffff0000, v59
	v_pk_mul_f32 v[140:141], v[140:141], v[148:149]
	v_pk_mul_f32 v[146:147], v[146:147], v[56:57]
	v_cvt_pk_bf16_f32 v56, v140, v141
	v_cvt_pk_bf16_f32 v57, v142, v143
	v_cvt_pk_bf16_f32 v58, v144, v145
	v_cvt_pk_bf16_f32 v59, v146, v147
	ds_read_u16 v139, v81
	ds_read_u16 v144, v81 offset:64
	ds_read_u16 v140, v80 offset:4624
	ds_read_u16 v145, v80 offset:4688
	ds_read_u16 v141, v80 offset:4896
	ds_read_u16 v146, v80 offset:4960
	ds_read_u16 v147, v80 offset:5168
	ds_read_u16 v148, v80 offset:5232
	ds_read_u16 v142, v80 offset:5440
	ds_read_u16 v149, v80 offset:5504
	ds_read_u16 v150, v80 offset:5712
	ds_read_u16 v151, v80 offset:5776
	ds_read_u16 v143, v80 offset:5984
	ds_read_u16 v152, v80 offset:6048
	ds_read_u16 v153, v80 offset:6256
	ds_read_u16 v154, v80 offset:6320
	s_waitcnt lgkmcnt(5)
	v_perm_b32 v142, v150, v142, s48
	v_perm_b32 v141, v147, v141, s48
	v_perm_b32 v140, v140, v139, s48
	s_waitcnt lgkmcnt(1)
	v_perm_b32 v143, v153, v143, s48
	s_add_i32 s8, s8, s9
	s_add_i32 s10, s10, s11
	v_mfma_f32_32x32x16_bf16 v[16:31], v[56:59], v[140:143], v[16:31]
	s_waitcnt lgkmcnt(0)
	v_perm_b32 v143, v154, v152, s48
	v_perm_b32 v142, v151, v149, s48
	v_perm_b32 v141, v148, v146, s48
	v_perm_b32 v140, v145, v144, s48
	s_waitcnt vmcnt(37)
	v_lshlrev_b32_e32 v144, 16, v52
	v_and_b32_e32 v145, 0xffff0000, v52
	v_lshlrev_b32_e32 v52, 16, v53
	v_mfma_f32_32x32x16_bf16 v[0:15], v[56:59], v[140:143], v[0:15]
	ds_read_b128 v[56:59], v79 offset:34944
	ds_read_b128 v[140:143], v79 offset:34960
	v_and_b32_e32 v53, 0xffff0000, v53
	s_cmpk_lt_i32 s6, 0x300
	s_waitcnt lgkmcnt(1)
	v_pk_mul_f32 v[58:59], v[58:59], v[52:53]
	v_lshlrev_b32_e32 v52, 16, v54
	v_and_b32_e32 v53, 0xffff0000, v54
	s_waitcnt lgkmcnt(0)
	v_pk_mul_f32 v[140:141], v[140:141], v[52:53]
	v_lshlrev_b32_e32 v52, 16, v55
	v_and_b32_e32 v53, 0xffff0000, v55
	v_pk_mul_f32 v[56:57], v[56:57], v[144:145]
	v_pk_mul_f32 v[142:143], v[142:143], v[52:53]
	v_cvt_pk_bf16_f32 v52, v56, v57
	v_cvt_pk_bf16_f32 v53, v58, v59
	v_cvt_pk_bf16_f32 v54, v140, v141
	v_cvt_pk_bf16_f32 v55, v142, v143
	ds_read_u16 v56, v82
	ds_read_u16 v139, v82 offset:64
	ds_read_u16 v140, v80 offset:8976
	ds_read_u16 v141, v80 offset:9040
	ds_read_u16 v57, v80 offset:9248
	ds_read_u16 v142, v80 offset:9312
	ds_read_u16 v143, v80 offset:9520
	ds_read_u16 v144, v80 offset:9584
	ds_read_u16 v58, v80 offset:9792
	ds_read_u16 v145, v80 offset:9856
	ds_read_u16 v146, v80 offset:10064
	ds_read_u16 v147, v80 offset:10128
	ds_read_u16 v59, v80 offset:10336
	ds_read_u16 v148, v80 offset:10400
	ds_read_u16 v149, v80 offset:10608
	ds_read_u16 v150, v80 offset:10672
	s_waitcnt lgkmcnt(5)
	v_perm_b32 v58, v146, v58, s48
	v_perm_b32 v57, v143, v57, s48
	v_perm_b32 v56, v140, v56, s48
	s_waitcnt lgkmcnt(1)
	v_perm_b32 v59, v149, v59, s48
	s_waitcnt vmcnt(36)
	v_lshlrev_b32_e32 v140, 16, v48
	v_mfma_f32_32x32x16_bf16 v[16:31], v[52:55], v[56:59], v[16:31]
	s_waitcnt lgkmcnt(0)
	v_perm_b32 v59, v150, v148, s48
	v_perm_b32 v58, v147, v145, s48
	v_perm_b32 v57, v144, v142, s48
	v_perm_b32 v56, v141, v139, s48
	v_and_b32_e32 v141, 0xffff0000, v48
	v_lshlrev_b32_e32 v48, 16, v49
	v_and_b32_e32 v49, 0xffff0000, v49
	v_mfma_f32_32x32x16_bf16 v[0:15], v[52:55], v[56:59], v[0:15]
	ds_read_b128 v[52:55], v79 offset:35008
	ds_read_b128 v[56:59], v79 offset:35024
	s_waitcnt lgkmcnt(1)
	v_mul_f32_e64 v54, v54, v48
	v_mul_f32_e64 v55, v55, v49
	v_lshlrev_b32_e32 v48, 16, v50
	v_and_b32_e32 v49, 0xffff0000, v50
	s_waitcnt lgkmcnt(0)
	v_pk_mul_f32 v[56:57], v[56:57], v[48:49]
	v_lshlrev_b32_e32 v48, 16, v51
	v_and_b32_e32 v49, 0xffff0000, v51
	v_pk_mul_f32 v[52:53], v[52:53], v[140:141]
	v_pk_mul_f32 v[58:59], v[58:59], v[48:49]
	v_cvt_pk_bf16_f32 v48, v52, v53
	v_cvt_pk_bf16_f32 v49, v54, v55
	v_cvt_pk_bf16_f32 v50, v56, v57
	v_cvt_pk_bf16_f32 v51, v58, v59
	ds_read_u16 v52, v83
	ds_read_u16 v56, v83 offset:64
	ds_read_u16 v57, v80 offset:13328
	ds_read_u16 v58, v80 offset:13392
	ds_read_u16 v53, v80 offset:13600
	ds_read_u16 v59, v80 offset:13664
	ds_read_u16 v139, v80 offset:13872
	ds_read_u16 v140, v80 offset:13936
	ds_read_u16 v54, v80 offset:14144
	ds_read_u16 v141, v80 offset:14208
	ds_read_u16 v142, v80 offset:14416
	ds_read_u16 v143, v80 offset:14480
	ds_read_u16 v55, v80 offset:14688
	ds_read_u16 v144, v80 offset:14752
	ds_read_u16 v145, v80 offset:14960
	ds_read_u16 v146, v80 offset:15024
	s_waitcnt lgkmcnt(5)
	v_perm_b32 v54, v142, v54, s48
	v_perm_b32 v53, v139, v53, s48
	v_perm_b32 v52, v57, v52, s48
	s_waitcnt lgkmcnt(1)
	v_perm_b32 v55, v145, v55, s48
	s_waitcnt vmcnt(35)
	v_and_b32_e32 v57, 0xffff0000, v44
	v_mfma_f32_32x32x16_bf16 v[16:31], v[48:51], v[52:55], v[16:31]
	s_waitcnt lgkmcnt(0)
	v_perm_b32 v55, v146, v144, s48
	v_perm_b32 v54, v143, v141, s48
	v_perm_b32 v53, v140, v59, s48
	v_perm_b32 v52, v58, v56, s48
	v_lshlrev_b32_e32 v56, 16, v44
	v_lshlrev_b32_e32 v44, 16, v45
	v_and_b32_e32 v45, 0xffff0000, v45
	v_mfma_f32_32x32x16_bf16 v[0:15], v[48:51], v[52:55], v[0:15]
	ds_read_b128 v[48:51], v79 offset:35072
	ds_read_b128 v[52:55], v79 offset:35088
	s_waitcnt lgkmcnt(1)
	v_mul_f32_e64 v50, v50, v44
	v_mul_f32_e64 v51, v51, v45
	v_lshlrev_b32_e32 v44, 16, v46
	v_and_b32_e32 v45, 0xffff0000, v46
	s_waitcnt lgkmcnt(0)
	v_pk_mul_f32 v[52:53], v[52:53], v[44:45]
	v_lshlrev_b32_e32 v44, 16, v47
	v_and_b32_e32 v45, 0xffff0000, v47
	v_pk_mul_f32 v[48:49], v[48:49], v[56:57]
	v_pk_mul_f32 v[54:55], v[54:55], v[44:45]
	v_cvt_pk_bf16_f32 v44, v48, v49
	v_cvt_pk_bf16_f32 v45, v50, v51
	v_cvt_pk_bf16_f32 v46, v52, v53
	v_cvt_pk_bf16_f32 v47, v54, v55
	ds_read_u16 v48, v84
	ds_read_u16 v52, v84 offset:64
	ds_read_u16 v53, v80 offset:17680
	ds_read_u16 v54, v80 offset:17744
	ds_read_u16 v49, v80 offset:17952
	ds_read_u16 v55, v80 offset:18016
	ds_read_u16 v56, v80 offset:18224
	ds_read_u16 v57, v80 offset:18288
	ds_read_u16 v50, v80 offset:18496
	ds_read_u16 v58, v80 offset:18560
	ds_read_u16 v59, v80 offset:18768
	ds_read_u16 v139, v80 offset:18832
	ds_read_u16 v51, v80 offset:19040
	ds_read_u16 v140, v80 offset:19104
	ds_read_u16 v141, v80 offset:19312
	ds_read_u16 v142, v80 offset:19376
	s_waitcnt lgkmcnt(5)
	v_perm_b32 v50, v59, v50, s48
	v_perm_b32 v49, v56, v49, s48
	v_perm_b32 v48, v53, v48, s48
	s_waitcnt lgkmcnt(1)
	v_perm_b32 v51, v141, v51, s48
	s_waitcnt vmcnt(34)
	v_and_b32_e32 v53, 0xffff0000, v40
	v_mfma_f32_32x32x16_bf16 v[16:31], v[44:47], v[48:51], v[16:31]
	s_waitcnt lgkmcnt(0)
	v_perm_b32 v51, v142, v140, s48
	v_perm_b32 v50, v139, v58, s48
	v_perm_b32 v49, v57, v55, s48
	v_perm_b32 v48, v54, v52, s48
	v_lshlrev_b32_e32 v52, 16, v40
	v_lshlrev_b32_e32 v40, 16, v41
	v_and_b32_e32 v41, 0xffff0000, v41
	v_mfma_f32_32x32x16_bf16 v[0:15], v[44:47], v[48:51], v[0:15]
	ds_read_b128 v[44:47], v79 offset:35136
	ds_read_b128 v[48:51], v79 offset:35152
	s_waitcnt lgkmcnt(1)
	v_mul_f32_e64 v46, v46, v40
	v_mul_f32_e64 v47, v47, v41
	v_lshlrev_b32_e32 v40, 16, v42
	v_and_b32_e32 v41, 0xffff0000, v42
	s_waitcnt lgkmcnt(0)
	v_pk_mul_f32 v[48:49], v[48:49], v[40:41]
	v_lshlrev_b32_e32 v40, 16, v43
	v_and_b32_e32 v41, 0xffff0000, v43
	v_pk_mul_f32 v[44:45], v[44:45], v[52:53]
	v_pk_mul_f32 v[50:51], v[50:51], v[40:41]
	v_cvt_pk_bf16_f32 v40, v44, v45
	v_cvt_pk_bf16_f32 v41, v46, v47
	v_cvt_pk_bf16_f32 v42, v48, v49
	v_cvt_pk_bf16_f32 v43, v50, v51
	ds_read_u16 v44, v85
	ds_read_u16 v48, v85 offset:64
	ds_read_u16 v49, v80 offset:22032
	ds_read_u16 v50, v80 offset:22096
	ds_read_u16 v45, v80 offset:22304
	ds_read_u16 v51, v80 offset:22368
	ds_read_u16 v52, v80 offset:22576
	ds_read_u16 v53, v80 offset:22640
	ds_read_u16 v46, v80 offset:22848
	ds_read_u16 v54, v80 offset:22912
	ds_read_u16 v55, v80 offset:23120
	ds_read_u16 v56, v80 offset:23184
	ds_read_u16 v47, v80 offset:23392
	ds_read_u16 v57, v80 offset:23456
	ds_read_u16 v58, v80 offset:23664
	ds_read_u16 v59, v80 offset:23728
	s_waitcnt lgkmcnt(5)
	v_perm_b32 v46, v55, v46, s48
	v_perm_b32 v45, v52, v45, s48
	v_perm_b32 v44, v49, v44, s48
	s_waitcnt lgkmcnt(1)
	v_perm_b32 v47, v58, v47, s48
	s_waitcnt vmcnt(33)
	v_and_b32_e32 v49, 0xffff0000, v36
	v_mfma_f32_32x32x16_bf16 v[16:31], v[40:43], v[44:47], v[16:31]
	s_waitcnt lgkmcnt(0)
	v_perm_b32 v47, v59, v57, s48
	v_perm_b32 v46, v56, v54, s48
	v_perm_b32 v45, v53, v51, s48
	v_perm_b32 v44, v50, v48, s48
	v_lshlrev_b32_e32 v48, 16, v36
	v_lshlrev_b32_e32 v36, 16, v37
	v_and_b32_e32 v37, 0xffff0000, v37
	v_mfma_f32_32x32x16_bf16 v[0:15], v[40:43], v[44:47], v[0:15]
	ds_read_b128 v[40:43], v79 offset:35200
	ds_read_b128 v[44:47], v79 offset:35216
	s_waitcnt lgkmcnt(1)
	v_mul_f32_e64 v42, v42, v36
	v_mul_f32_e64 v43, v43, v37
	v_lshlrev_b32_e32 v36, 16, v38
	v_and_b32_e32 v37, 0xffff0000, v38
	s_waitcnt lgkmcnt(0)
	v_pk_mul_f32 v[44:45], v[44:45], v[36:37]
	v_lshlrev_b32_e32 v36, 16, v39
	v_and_b32_e32 v37, 0xffff0000, v39
	v_pk_mul_f32 v[40:41], v[40:41], v[48:49]
	v_pk_mul_f32 v[46:47], v[46:47], v[36:37]
	v_cvt_pk_bf16_f32 v36, v40, v41
	v_cvt_pk_bf16_f32 v37, v42, v43
	v_cvt_pk_bf16_f32 v38, v44, v45
	v_cvt_pk_bf16_f32 v39, v46, v47
	ds_read_u16 v40, v86
	ds_read_u16 v44, v86 offset:64
	ds_read_u16 v45, v80 offset:26384
	ds_read_u16 v46, v80 offset:26448
	ds_read_u16 v41, v80 offset:26656
	ds_read_u16 v47, v80 offset:26720
	ds_read_u16 v48, v80 offset:26928
	ds_read_u16 v49, v80 offset:26992
	ds_read_u16 v42, v80 offset:27200
	ds_read_u16 v50, v80 offset:27264
	ds_read_u16 v51, v80 offset:27472
	ds_read_u16 v52, v80 offset:27536
	ds_read_u16 v43, v80 offset:27744
	ds_read_u16 v53, v80 offset:27808
	ds_read_u16 v54, v80 offset:28016
	ds_read_u16 v55, v80 offset:28080
	s_waitcnt lgkmcnt(5)
	v_perm_b32 v42, v51, v42, s48
	v_perm_b32 v41, v48, v41, s48
	v_perm_b32 v40, v45, v40, s48
	s_waitcnt lgkmcnt(1)
	v_perm_b32 v43, v54, v43, s48
	s_waitcnt vmcnt(32)
	v_and_b32_e32 v45, 0xffff0000, v32
	v_mfma_f32_32x32x16_bf16 v[16:31], v[36:39], v[40:43], v[16:31]
	s_waitcnt lgkmcnt(0)
	v_perm_b32 v43, v55, v53, s48
	v_perm_b32 v42, v52, v50, s48
	v_perm_b32 v41, v49, v47, s48
	v_perm_b32 v40, v46, v44, s48
	v_lshlrev_b32_e32 v44, 16, v32
	v_lshlrev_b32_e32 v32, 16, v33
	v_and_b32_e32 v33, 0xffff0000, v33
	v_mfma_f32_32x32x16_bf16 v[0:15], v[36:39], v[40:43], v[0:15]
	ds_read_b128 v[36:39], v79 offset:35264
	ds_read_b128 v[40:43], v79 offset:35280
	s_waitcnt lgkmcnt(1)
	v_mul_f32_e64 v38, v38, v32
	v_mul_f32_e64 v39, v39, v33
	v_lshlrev_b32_e32 v32, 16, v34
	v_and_b32_e32 v33, 0xffff0000, v34
	s_waitcnt lgkmcnt(0)
	v_pk_mul_f32 v[40:41], v[40:41], v[32:33]
	v_lshlrev_b32_e32 v32, 16, v35
	v_and_b32_e32 v33, 0xffff0000, v35
	v_pk_mul_f32 v[36:37], v[36:37], v[44:45]
	v_pk_mul_f32 v[42:43], v[42:43], v[32:33]
	v_cvt_pk_bf16_f32 v32, v36, v37
	v_cvt_pk_bf16_f32 v33, v38, v39
	v_cvt_pk_bf16_f32 v34, v40, v41
	v_cvt_pk_bf16_f32 v35, v42, v43
	ds_read_u16 v36, v87
	ds_read_u16 v40, v87 offset:64
	ds_read_u16 v41, v80 offset:30736
	ds_read_u16 v42, v80 offset:30800
	ds_read_u16 v37, v80 offset:31008
	ds_read_u16 v43, v80 offset:31072
	ds_read_u16 v44, v80 offset:31280
	ds_read_u16 v45, v80 offset:31344
	ds_read_u16 v38, v80 offset:31552
	ds_read_u16 v46, v80 offset:31616
	ds_read_u16 v47, v80 offset:31824
	ds_read_u16 v48, v80 offset:31888
	ds_read_u16 v39, v80 offset:32096
	ds_read_u16 v49, v80 offset:32160
	ds_read_u16 v50, v80 offset:32368
	ds_read_u16 v51, v80 offset:32432
	s_waitcnt lgkmcnt(5)
	v_perm_b32 v38, v47, v38, s48
	v_perm_b32 v37, v44, v37, s48
	v_perm_b32 v36, v41, v36, s48
	s_waitcnt lgkmcnt(1)
	v_perm_b32 v39, v50, v39, s48
	s_waitcnt vmcnt(30)
	v_lshlrev_b32_e32 v44, 16, v138
	v_mfma_f32_32x32x16_bf16 v[16:31], v[32:35], v[36:39], v[16:31]
	s_waitcnt lgkmcnt(0)
	v_perm_b32 v39, v51, v49, s48
	v_perm_b32 v38, v48, v46, s48
	v_perm_b32 v37, v45, v43, s48
	v_perm_b32 v36, v42, v40, s48
	v_lshlrev_b32_e32 v42, 16, v137
	s_nop 0
	v_mfma_f32_32x32x16_bf16 v[0:15], v[32:35], v[36:39], v[0:15]
	v_mov_b32_e32 v32, s0
	ds_read_b64 v[32:33], v32
	v_add_u32_e32 v38, s13, v73
	v_ashrrev_i32_e32 v39, 31, v38
	s_waitcnt lgkmcnt(0)
	v_readfirstlane_b32 s0, v32
	v_or_b32_e32 v32, s13, v74
	v_readfirstlane_b32 s1, v33
	v_lshlrev_b32_e32 v32, 2, v32
	s_nop 3
	global_load_dword v37, v32, s[0:1]
	global_load_dword v36, v32, s[0:1] offset:128
	v_readlane_b32 s0, v254, 30
	s_nop 1
	v_mov_b32_e32 v32, s0
	ds_read_b64 v[34:35], v32
	v_lshl_add_u64 v[32:33], v[66:67], 0, s[96:97]
	s_waitcnt lgkmcnt(0)
	v_readfirstlane_b32 s0, v35
	v_readfirstlane_b32 s1, v34
	s_nop 0
	v_mov_b32_e32 v35, s0
	v_mov_b32_e32 v34, s1
	v_lshl_add_u64 v[34:35], v[38:39], 2, v[34:35]
	global_load_dwordx4 v[38:41], v[34:35], off
	global_load_dwordx4 v[48:51], v[34:35], off offset:32
	global_load_dwordx4 v[52:55], v[34:35], off offset:64
	global_load_dwordx4 v[56:59], v[34:35], off offset:96
	s_waitcnt vmcnt(0)
	v_fma_f32 v16, v16, v37, v38
	v_fma_f32 v0, v0, v36, v38
	v_mul_f32_e32 v16, v16, v42
	v_mul_f32_e32 v0, v0, v44
	v_cvt_pk_bf16_f32 v16, v16, s0
	v_lshl_add_u64 v[42:43], v[32:33], 0, v[68:69]
	v_cvt_pk_bf16_f32 v0, v0, s0
	global_store_short v[42:43], v16, off
	global_store_short v[42:43], v0, off offset:64
	v_add_u32_e32 v42, s12, v88
	v_ashrrev_i32_e32 v43, 31, v42
	v_lshlrev_b32_e32 v0, 16, v135
	v_fma_f32 v16, v17, v37, v39
	v_mul_f32_e32 v0, v16, v0
	v_lshlrev_b64 v[16:17], 11, v[42:43]
	v_cvt_pk_bf16_f32 v0, v0, s0
	v_lshl_add_u64 v[16:17], v[32:33], 0, v[16:17]
	v_lshlrev_b32_e32 v38, 16, v136
	global_store_short v[16:17], v0, off
	v_fma_f32 v0, v1, v36, v39
	v_mul_f32_e32 v0, v0, v38
	v_cvt_pk_bf16_f32 v0, v0, s0
	global_store_short v[16:17], v0, off offset:64
	v_add_u32_e32 v0, s12, v89
	v_ashrrev_i32_e32 v1, 31, v0
	v_lshlrev_b32_e32 v16, 16, v133
	v_lshlrev_b32_e32 v17, 16, v134
	v_fma_f32 v18, v18, v37, v40
	v_fma_f32 v2, v2, v36, v40
	v_mul_f32_e32 v16, v18, v16
	v_lshlrev_b64 v[0:1], 11, v[0:1]
	v_mul_f32_e32 v2, v2, v17
	v_cvt_pk_bf16_f32 v16, v16, s0
	v_lshl_add_u64 v[0:1], v[32:33], 0, v[0:1]
	v_cvt_pk_bf16_f32 v2, v2, s0
	global_store_short v[0:1], v16, off
	global_store_short v[0:1], v2, off offset:64
	v_add_u32_e32 v0, s12, v90
	v_ashrrev_i32_e32 v1, 31, v0
	v_lshlrev_b32_e32 v2, 16, v131
	v_fma_f32 v17, v19, v37, v41
	v_mul_f32_e32 v2, v17, v2
	v_lshlrev_b64 v[0:1], 11, v[0:1]
	v_lshlrev_b32_e32 v16, 16, v132
	v_cvt_pk_bf16_f32 v2, v2, s0
	v_lshl_add_u64 v[0:1], v[32:33], 0, v[0:1]
	v_fmac_f32_e32 v41, v3, v36
	global_store_short v[0:1], v2, off
	v_mul_f32_e32 v2, v41, v16
	v_cvt_pk_bf16_f32 v2, v2, s0
	global_store_short v[0:1], v2, off offset:64
	v_mov_b32_e32 v0, v48
	v_mov_b32_e32 v1, v49
	v_mov_b32_e32 v2, v50
	v_mov_b32_e32 v3, v51
	v_add_u32_e32 v16, s12, v91
	v_ashrrev_i32_e32 v17, 31, v16
	v_lshlrev_b32_e32 v18, 16, v129
	v_lshlrev_b32_e32 v19, 16, v130
	v_lshlrev_b64 v[16:17], 11, v[16:17]
	v_lshl_add_u64 v[16:17], v[32:33], 0, v[16:17]
	s_nop 0
	v_fma_f32 v20, v20, v37, v0
	v_fma_f32 v0, v4, v36, v0
	v_mul_f32_e32 v18, v20, v18
	v_mul_f32_e32 v0, v0, v19
	v_cvt_pk_bf16_f32 v18, v18, s0
	v_cvt_pk_bf16_f32 v0, v0, s0
	global_store_short v[16:17], v18, off
	global_store_short v[16:17], v0, off offset:64
	v_add_u32_e32 v16, s12, v92
	v_ashrrev_i32_e32 v17, 31, v16
	v_lshlrev_b32_e32 v0, 16, v127
	v_fma_f32 v18, v21, v37, v1
	v_mul_f32_e32 v0, v18, v0
	v_lshlrev_b64 v[16:17], 11, v[16:17]
	v_cvt_pk_bf16_f32 v0, v0, s0
	v_lshl_add_u64 v[16:17], v[32:33], 0, v[16:17]
	v_lshlrev_b32_e32 v4, 16, v128
	global_store_short v[16:17], v0, off
	v_fma_f32 v0, v5, v36, v1
	v_mul_f32_e32 v0, v0, v4
	v_cvt_pk_bf16_f32 v0, v0, s0
	global_store_short v[16:17], v0, off offset:64
	v_add_u32_e32 v0, s12, v93
	v_ashrrev_i32_e32 v1, 31, v0
	v_lshlrev_b32_e32 v4, 16, v125
	v_lshlrev_b32_e32 v5, 16, v126
	v_fma_f32 v16, v22, v37, v2
	v_fma_f32 v2, v6, v36, v2
	v_mul_f32_e32 v4, v16, v4
	v_lshlrev_b64 v[0:1], 11, v[0:1]
	v_mul_f32_e32 v2, v2, v5
	v_cvt_pk_bf16_f32 v4, v4, s0
	v_lshl_add_u64 v[0:1], v[32:33], 0, v[0:1]
	v_cvt_pk_bf16_f32 v2, v2, s0
	global_store_short v[0:1], v4, off
	global_store_short v[0:1], v2, off offset:64
	v_add_u32_e32 v0, s12, v94
	v_ashrrev_i32_e32 v1, 31, v0
	v_lshlrev_b32_e32 v2, 16, v123
	v_fma_f32 v5, v23, v37, v3
	v_mul_f32_e32 v2, v5, v2
	v_lshlrev_b64 v[0:1], 11, v[0:1]
	v_lshlrev_b32_e32 v4, 16, v124
	v_cvt_pk_bf16_f32 v2, v2, s0
	v_lshl_add_u64 v[0:1], v[32:33], 0, v[0:1]
	v_fmac_f32_e32 v3, v7, v36
	global_store_short v[0:1], v2, off
	v_mul_f32_e32 v2, v3, v4
	v_cvt_pk_bf16_f32 v2, v2, s0
	global_store_short v[0:1], v2, off offset:64
	v_mov_b32_e32 v0, v52
	v_mov_b32_e32 v1, v53
	v_mov_b32_e32 v2, v54
	v_mov_b32_e32 v3, v55
	v_add_u32_e32 v4, s12, v95
	v_ashrrev_i32_e32 v5, 31, v4
	v_lshlrev_b32_e32 v6, 16, v121
	v_lshlrev_b32_e32 v7, 16, v122
	v_lshlrev_b64 v[4:5], 11, v[4:5]
	v_lshl_add_u64 v[4:5], v[32:33], 0, v[4:5]
	s_nop 0
	v_fma_f32 v16, v24, v37, v0
	v_fma_f32 v0, v8, v36, v0
	v_mul_f32_e32 v6, v16, v6
	v_mul_f32_e32 v0, v0, v7
	v_cvt_pk_bf16_f32 v6, v6, s0
	v_cvt_pk_bf16_f32 v0, v0, s0
	global_store_short v[4:5], v6, off
	global_store_short v[4:5], v0, off offset:64
	v_add_u32_e32 v4, s12, v96
	v_ashrrev_i32_e32 v5, 31, v4
	v_lshlrev_b32_e32 v0, 16, v119
	v_fma_f32 v7, v25, v37, v1
	v_mul_f32_e32 v0, v7, v0
	v_lshlrev_b64 v[4:5], 11, v[4:5]
	v_cvt_pk_bf16_f32 v0, v0, s0
	v_lshl_add_u64 v[4:5], v[32:33], 0, v[4:5]
	v_lshlrev_b32_e32 v6, 16, v120
	global_store_short v[4:5], v0, off
	v_fma_f32 v0, v9, v36, v1
	v_mul_f32_e32 v0, v0, v6
	v_cvt_pk_bf16_f32 v0, v0, s0
	global_store_short v[4:5], v0, off offset:64
	v_add_u32_e32 v0, s12, v97
	v_ashrrev_i32_e32 v1, 31, v0
	v_lshlrev_b32_e32 v4, 16, v117
	v_lshlrev_b32_e32 v5, 16, v118
	v_fma_f32 v6, v26, v37, v2
	v_fma_f32 v2, v10, v36, v2
	v_mul_f32_e32 v4, v6, v4
	v_lshlrev_b64 v[0:1], 11, v[0:1]
	v_mul_f32_e32 v2, v2, v5
	v_cvt_pk_bf16_f32 v4, v4, s0
	v_lshl_add_u64 v[0:1], v[32:33], 0, v[0:1]
	v_cvt_pk_bf16_f32 v2, v2, s0
	global_store_short v[0:1], v4, off
	global_store_short v[0:1], v2, off offset:64
	v_add_u32_e32 v0, s12, v98
	v_ashrrev_i32_e32 v1, 31, v0
	v_lshlrev_b32_e32 v2, 16, v115
	v_fma_f32 v5, v27, v37, v3
	v_mul_f32_e32 v2, v5, v2
	v_lshlrev_b64 v[0:1], 11, v[0:1]
	v_lshlrev_b32_e32 v4, 16, v116
	v_cvt_pk_bf16_f32 v2, v2, s0
	v_lshl_add_u64 v[0:1], v[32:33], 0, v[0:1]
	v_fmac_f32_e32 v3, v11, v36
	global_store_short v[0:1], v2, off
	v_mul_f32_e32 v2, v3, v4
	v_cvt_pk_bf16_f32 v2, v2, s0
	global_store_short v[0:1], v2, off offset:64
	v_mov_b32_e32 v0, v56
	v_mov_b32_e32 v1, v57
	v_mov_b32_e32 v2, v58
	v_mov_b32_e32 v3, v59
	v_add_u32_e32 v4, s12, v99
	v_ashrrev_i32_e32 v5, 31, v4
	v_lshlrev_b32_e32 v6, 16, v113
	v_lshlrev_b32_e32 v7, 16, v114
	v_lshlrev_b64 v[4:5], 11, v[4:5]
	v_lshl_add_u64 v[4:5], v[32:33], 0, v[4:5]
	s_nop 0
	v_fma_f32 v8, v28, v37, v0
	v_fma_f32 v0, v12, v36, v0
	v_mul_f32_e32 v6, v8, v6
	v_mul_f32_e32 v0, v0, v7
	v_cvt_pk_bf16_f32 v6, v6, s0
	v_cvt_pk_bf16_f32 v0, v0, s0
	global_store_short v[4:5], v6, off
	global_store_short v[4:5], v0, off offset:64
	v_add_u32_e32 v4, s12, v100
	v_ashrrev_i32_e32 v5, 31, v4
	v_lshlrev_b32_e32 v0, 16, v111
	v_fma_f32 v7, v29, v37, v1
	v_mul_f32_e32 v0, v7, v0
	v_lshlrev_b64 v[4:5], 11, v[4:5]
	v_cvt_pk_bf16_f32 v0, v0, s0
	v_lshl_add_u64 v[4:5], v[32:33], 0, v[4:5]
	v_lshlrev_b32_e32 v6, 16, v112
	global_store_short v[4:5], v0, off
	v_fma_f32 v0, v13, v36, v1
	v_mul_f32_e32 v0, v0, v6
	v_cvt_pk_bf16_f32 v0, v0, s0
	global_store_short v[4:5], v0, off offset:64
	v_add_u32_e32 v0, s12, v101
	v_ashrrev_i32_e32 v1, 31, v0
	v_lshlrev_b32_e32 v4, 16, v109
	v_lshlrev_b32_e32 v5, 16, v110
	v_fma_f32 v6, v30, v37, v2
	v_fma_f32 v2, v14, v36, v2
	v_mul_f32_e32 v4, v6, v4
	v_lshlrev_b64 v[0:1], 11, v[0:1]
	v_mul_f32_e32 v2, v2, v5
	v_cvt_pk_bf16_f32 v4, v4, s0
	v_lshl_add_u64 v[0:1], v[32:33], 0, v[0:1]
	v_cvt_pk_bf16_f32 v2, v2, s0
	global_store_short v[0:1], v4, off
	global_store_short v[0:1], v2, off offset:64
	v_add_u32_e32 v0, s12, v102
	v_ashrrev_i32_e32 v1, 31, v0
	v_lshlrev_b32_e32 v2, 16, v107
	v_fma_f32 v5, v31, v37, v3
	v_mul_f32_e32 v2, v5, v2
	v_lshlrev_b64 v[0:1], 11, v[0:1]
	v_lshlrev_b32_e32 v4, 16, v108
	v_cvt_pk_bf16_f32 v2, v2, s0
	v_lshl_add_u64 v[0:1], v[32:33], 0, v[0:1]
	v_fmac_f32_e32 v3, v15, v36
	global_store_short v[0:1], v2, off
	v_mul_f32_e32 v2, v3, v4
	v_cvt_pk_bf16_f32 v2, v2, s0
	global_store_short v[0:1], v2, off offset:64
	s_barrier
	s_cbranch_scc0 .LBB0_218
.LBB0_216:
	s_and_b32 s12, s10, 0xffffff80
	s_and_b32 s13, s8, 0x380
	s_lshl_b32 s96, s13, 1
	v_lshl_add_u64 v[4:5], v[60:61], 0, s[96:97]
	v_add_u32_e32 v0, s12, v75
	v_ashrrev_i32_e32 v1, 31, v0
	v_lshlrev_b64 v[0:1], 11, v[0:1]
	v_lshl_add_u64 v[0:1], v[4:5], 0, v[0:1]
	global_load_dwordx4 v[8:11], v[0:1], off nt
	v_add_u32_e32 v0, s12, v76
	v_ashrrev_i32_e32 v1, 31, v0
	v_lshlrev_b64 v[0:1], 11, v[0:1]
	v_lshl_add_u64 v[0:1], v[4:5], 0, v[0:1]
	global_load_dwordx4 v[12:15], v[0:1], off nt
	v_add_u32_e32 v0, s12, v77
	v_ashrrev_i32_e32 v1, 31, v0
	v_lshlrev_b64 v[0:1], 11, v[0:1]
	v_lshl_add_u64 v[0:1], v[4:5], 0, v[0:1]
	global_load_dwordx4 v[16:19], v[0:1], off nt
	v_add_u32_e32 v0, s12, v78
	v_ashrrev_i32_e32 v1, 31, v0
	v_lshlrev_b64 v[0:1], 11, v[0:1]
	v_lshl_add_u64 v[0:1], v[4:5], 0, v[0:1]
	global_load_dwordx4 v[20:23], v[0:1], off nt
	s_and_saveexec_b64 s[2:3], vcc
	s_cbranch_execz .Lsp_norss
	v_add_u32_e32 v0, s12, v70
	v_ashrrev_i32_e32 v1, 31, v0
	v_lshl_add_u64 v[0:1], v[0:1], 2, s[4:5]
	global_load_dword v6, v[0:1], off
.Lsp_norss:
	s_or_b64 exec, exec, s[2:3]
	s_waitcnt vmcnt(0)
	ds_write_b128 v103, v[8:11]
	ds_write_b128 v104, v[12:15]
	ds_write_b128 v105, v[16:19]
	ds_write_b128 v106, v[20:23]
	s_and_saveexec_b64 s[2:3], vcc
	s_cbranch_execz .LBB0_215
	v_fmamk_f32 v0, v6, 0x3a800000, v225
	v_mul_f32_e32 v1, 0x4b800000, v0
	v_cmp_gt_f32_e64 s[0:1], s93, v0
	s_nop 1
	v_cndmask_b32_e64 v0, v0, v1, s[0:1]
	v_rsq_f32_e32 v0, v0
	s_nop 0
	v_mul_f32_e32 v1, 0x45800000, v0
	v_cndmask_b32_e64 v0, v0, v1, s[0:1]
	ds_write_b32 v71, v0 offset:34816
	s_branch .LBB0_215
